# dilated block: V and K tiles staged in LDS with full-line loads, QK fragments from LDS; sparse v3; indexer LDS-staged
# speedup vs baseline: 1.4330x; 1.0153x over previous
; #define LAS __attribute__((address_space(3)))
; __device__ __forceinline__ void dilated_block(const bf16_t* QKV, bf16_t* OG, float* LSE, LAS unsigned char* lds, int u, int tid) {
;     ...
;     __syncthreads();
; #pragma unroll
;     for (int i = 0; i < 8; ++i) { const int c = tid + 512 * i, row = c >> 4, ch = c & 15, m = mbase + row; u32x4 v = {0u, 0u, 0u, 0u};
;         if (m >= 0) v = *(const u32x4*)(QKV + (size_t)((m << rsh) + p) * QKVW + COL_AV + head * 128 + ch * 8);
;         *(LAS u32x4*)(lds + row * VRS + ch * 16) = v; }
;     __syncthreads();
;     const int i0 = wave * 16;
;     const int tq = ((mbase + 128 + i0 + n16) << rsh) + p;
;     bf16x8 qf[4];
; #pragma unroll
;     for (int ks = 0; ks < 4; ++ks) qf[ks] = *(const bf16x8*)(QKV + (size_t)tq * QKVW + COL_AQ + head * 128 + ks * 32 + slab * 8);
;     f32x4 sacc[10];
; #pragma unroll
;     for (int jt = 0; jt < 9; ++jt) { int m = mbase + i0 + 16 * jt + n16; m = max(m, 0);
;         const bf16_t* kp = QKV + (size_t)((m << rsh) + p) * QKVW + COL_AK + head * 128 + slab * 8;
.LBB0_197:
	s_ashr_i32 s0, s8, 9
	s_lshl_b32 s13, s0, 1
	s_lshr_b32 s4, 0x80, s13
	s_and_b32 s1, s8, 0x7f
	s_sub_i32 s5, 7, s13
	s_add_i32 s4, s4, -1
	s_lshr_b32 s19, s1, s5
	s_and_b32 s5, s4, s1
	s_bfe_u32 s9, s8, 0x20007
	s_lshl_b32 s1, s0, 2
	s_lshl_b32 s28, s5, 7
	s_or_b32 s4, s1, s9
	s_add_i32 s23, s28, 0xffffff80
	s_lshl_b32 s10, s4, 7
	v_add_u32_e32 v1, s23, v51
	s_ashr_i32 s11, s10, 31
	v_cmp_lt_i32_e32 vcc, -1, v1
	v_mov_b32_e32 v0, 0
	v_lshlrev_b32_e32 v6, 1, v48
	v_mov_b32_e32 v2, 0
	v_mov_b32_e32 v3, 0
	v_mov_b32_e32 v4, 0
	v_mov_b32_e32 v5, 0
	s_barrier
	v_mov_b32_e32 v7, v161
	s_movk_i32 s1, 0x3c00
	v_mov_b64_e32 v[94:95], 0
	v_mov_b64_e32 v[96:97], 0
	v_mov_b64_e32 v[130:131], 0
	v_mov_b64_e32 v[132:133], 0
	v_mov_b64_e32 v[98:99], 0
	v_mov_b64_e32 v[100:101], 0
	v_mov_b64_e32 v[134:135], 0
	v_mov_b64_e32 v[136:137], 0
	v_mov_b64_e32 v[102:103], 0
	v_mov_b64_e32 v[104:105], 0
	v_mov_b64_e32 v[138:139], 0
	v_mov_b64_e32 v[140:141], 0
	v_mov_b64_e32 v[106:107], 0
	v_mov_b64_e32 v[108:109], 0
	v_mov_b64_e32 v[142:143], 0
	v_mov_b64_e32 v[144:145], 0
	v_mov_b64_e32 v[110:111], 0
	v_mov_b64_e32 v[112:113], 0
	v_mov_b64_e32 v[146:147], 0
	v_mov_b64_e32 v[148:149], 0
	v_mov_b64_e32 v[114:115], 0
	v_mov_b64_e32 v[116:117], 0
	v_mov_b64_e32 v[150:151], 0
	v_mov_b64_e32 v[152:153], 0
	v_mov_b64_e32 v[118:119], 0
	v_mov_b64_e32 v[120:121], 0
	v_mov_b64_e32 v[196:197], 0
	v_mov_b64_e32 v[198:199], 0
	v_mov_b64_e32 v[122:123], 0
	v_mov_b64_e32 v[124:125], 0
	v_mov_b64_e32 v[184:185], 0
	v_mov_b64_e32 v[186:187], 0
	v_add_u32_e32 v126, s23, v51
	v_cmp_lt_i32_e32 vcc, -1, v126
	s_and_saveexec_b64 s[16:17], vcc
	v_lshlrev_b32_e32 v126, s13, v126
	v_add_u32_e32 v126, s19, v126
	v_mov_b64_e32 v[128:129], s[20:21]
	v_mad_i64_i32 v[128:129], s[34:35], v126, s1, v[128:129]
	v_lshl_add_u64 v[128:129], s[10:11], 1, v[128:129]
	v_lshl_add_u64 v[128:129], v[128:129], 0, v[6:7]
	v_add_co_u32_e32 v128, vcc, 0x1000, v128
	s_nop 1
	v_addc_co_u32_e32 v129, vcc, 0, v129, vcc
	global_load_dwordx4 v[94:97], v[128:129], off offset:2048
	global_load_dwordx4 v[130:133], v[128:129], off offset:-1024
	s_or_b64 exec, exec, s[16:17]
	v_add_u32_e32 v126, s23, v56
	v_cmp_lt_i32_e32 vcc, -1, v126
	s_and_saveexec_b64 s[16:17], vcc
	v_lshlrev_b32_e32 v126, s13, v126
	v_add_u32_e32 v126, s19, v126
	v_mov_b64_e32 v[128:129], s[20:21]
	v_mad_i64_i32 v[128:129], s[34:35], v126, s1, v[128:129]
	v_lshl_add_u64 v[128:129], s[10:11], 1, v[128:129]
	v_lshl_add_u64 v[128:129], v[128:129], 0, v[6:7]
	v_add_co_u32_e32 v128, vcc, 0x1000, v128
	s_nop 1
	v_addc_co_u32_e32 v129, vcc, 0, v129, vcc
	global_load_dwordx4 v[98:101], v[128:129], off offset:2048
	global_load_dwordx4 v[134:137], v[128:129], off offset:-1024
	s_or_b64 exec, exec, s[16:17]
	v_add_u32_e32 v126, s23, v57
	v_cmp_lt_i32_e32 vcc, -1, v126
	s_and_saveexec_b64 s[16:17], vcc
	v_lshlrev_b32_e32 v126, s13, v126
	v_add_u32_e32 v126, s19, v126
	v_mov_b64_e32 v[128:129], s[20:21]
	v_mad_i64_i32 v[128:129], s[34:35], v126, s1, v[128:129]
	v_lshl_add_u64 v[128:129], s[10:11], 1, v[128:129]
	v_lshl_add_u64 v[128:129], v[128:129], 0, v[6:7]
	v_add_co_u32_e32 v128, vcc, 0x1000, v128
	s_nop 1
	v_addc_co_u32_e32 v129, vcc, 0, v129, vcc
	global_load_dwordx4 v[102:105], v[128:129], off offset:2048
	global_load_dwordx4 v[138:141], v[128:129], off offset:-1024
	s_or_b64 exec, exec, s[16:17]
	v_add_u32_e32 v126, s23, v58
	v_cmp_lt_i32_e32 vcc, -1, v126
	s_and_saveexec_b64 s[16:17], vcc
	v_lshlrev_b32_e32 v126, s13, v126
	v_add_u32_e32 v126, s19, v126
	v_mov_b64_e32 v[128:129], s[20:21]
	v_mad_i64_i32 v[128:129], s[34:35], v126, s1, v[128:129]
	v_lshl_add_u64 v[128:129], s[10:11], 1, v[128:129]
	v_lshl_add_u64 v[128:129], v[128:129], 0, v[6:7]
	v_add_co_u32_e32 v128, vcc, 0x1000, v128
	s_nop 1
	v_addc_co_u32_e32 v129, vcc, 0, v129, vcc
	global_load_dwordx4 v[106:109], v[128:129], off offset:2048
	global_load_dwordx4 v[142:145], v[128:129], off offset:-1024
	s_or_b64 exec, exec, s[16:17]
	v_add_u32_e32 v126, s23, v59
	v_cmp_lt_i32_e32 vcc, -1, v126
	s_and_saveexec_b64 s[16:17], vcc
	v_lshlrev_b32_e32 v126, s13, v126
	v_add_u32_e32 v126, s19, v126
	v_mov_b64_e32 v[128:129], s[20:21]
	v_mad_i64_i32 v[128:129], s[34:35], v126, s1, v[128:129]
	v_lshl_add_u64 v[128:129], s[10:11], 1, v[128:129]
	v_lshl_add_u64 v[128:129], v[128:129], 0, v[6:7]
	v_add_co_u32_e32 v128, vcc, 0x1000, v128
	s_nop 1
	v_addc_co_u32_e32 v129, vcc, 0, v129, vcc
	global_load_dwordx4 v[110:113], v[128:129], off offset:2048
	global_load_dwordx4 v[146:149], v[128:129], off offset:-1024
	s_or_b64 exec, exec, s[16:17]
	v_add_u32_e32 v126, s23, v60
	v_cmp_lt_i32_e32 vcc, -1, v126
	s_and_saveexec_b64 s[16:17], vcc
	v_lshlrev_b32_e32 v126, s13, v126
	v_add_u32_e32 v126, s19, v126
	v_mov_b64_e32 v[128:129], s[20:21]
	v_mad_i64_i32 v[128:129], s[34:35], v126, s1, v[128:129]
	v_lshl_add_u64 v[128:129], s[10:11], 1, v[128:129]
	v_lshl_add_u64 v[128:129], v[128:129], 0, v[6:7]
	v_add_co_u32_e32 v128, vcc, 0x1000, v128
	s_nop 1
	v_addc_co_u32_e32 v129, vcc, 0, v129, vcc
	global_load_dwordx4 v[114:117], v[128:129], off offset:2048
	global_load_dwordx4 v[150:153], v[128:129], off offset:-1024
	s_or_b64 exec, exec, s[16:17]
	v_add_u32_e32 v126, s23, v61
	v_cmp_lt_i32_e32 vcc, -1, v126
	s_and_saveexec_b64 s[16:17], vcc
	v_lshlrev_b32_e32 v126, s13, v126
	v_add_u32_e32 v126, s19, v126
	v_mov_b64_e32 v[128:129], s[20:21]
	v_mad_i64_i32 v[128:129], s[34:35], v126, s1, v[128:129]
	v_lshl_add_u64 v[128:129], s[10:11], 1, v[128:129]
	v_lshl_add_u64 v[128:129], v[128:129], 0, v[6:7]
	v_add_co_u32_e32 v128, vcc, 0x1000, v128
	s_nop 1
	v_addc_co_u32_e32 v129, vcc, 0, v129, vcc
	global_load_dwordx4 v[118:121], v[128:129], off offset:2048
	global_load_dwordx4 v[196:199], v[128:129], off offset:-1024
	s_or_b64 exec, exec, s[16:17]
	v_add_u32_e32 v126, s23, v62
	v_cmp_lt_i32_e32 vcc, -1, v126
	s_and_saveexec_b64 s[16:17], vcc
	v_lshlrev_b32_e32 v126, s13, v126
	v_add_u32_e32 v126, s19, v126
	v_mov_b64_e32 v[128:129], s[20:21]
	v_mad_i64_i32 v[128:129], s[34:35], v126, s1, v[128:129]
	v_lshl_add_u64 v[128:129], s[10:11], 1, v[128:129]
	v_lshl_add_u64 v[128:129], v[128:129], 0, v[6:7]
	v_add_co_u32_e32 v128, vcc, 0x1000, v128
	s_nop 1
	v_addc_co_u32_e32 v129, vcc, 0, v129, vcc
	global_load_dwordx4 v[122:125], v[128:129], off offset:2048
	global_load_dwordx4 v[184:187], v[128:129], off offset:-1024
	s_or_b64 exec, exec, s[16:17]
	v_readfirstlane_b32 s1, v212
	s_ashr_i32 s22, s1, 2
	s_and_b32 s1, s22, -16
	s_add_i32 s16, s1, s28
	v_mov_b32_e32 v126, 70384
	v_mov_b32_e32 v127, 69632
	v_cmp_gt_u32_e32 vcc, 225, v62
	s_nop 1
	v_cndmask_b32_e32 v126, v126, v127, vcc
	v_add_u32_e32 v126, v126, v72
	s_waitcnt vmcnt(0)
; #define LAS __attribute__((address_space(3)))
; __device__ __forceinline__ void dilated_block(const bf16_t* QKV, bf16_t* OG, float* LSE, LAS unsigned char* lds, int u, int tid) {
;     ...
;     for (int i = 0; i < 8; ++i) { const int c = tid + 512 * i, row = c >> 4, ch = c & 15, m = mbase + row; u32x4 v = {0u, 0u, 0u, 0u};
;         if (m >= 0) v = *(const u32x4*)(QKV + (size_t)((m << rsh) + p) * QKVW + COL_AV + head * 128 + ch * 8);
;         *(LAS u32x4*)(lds + row * VRS + ch * 16) = v; }
;     __syncthreads();
;     const int i0 = wave * 16;
;     const int tq = ((mbase + 128 + i0 + n16) << rsh) + p;
;     bf16x8 qf[4];
; #pragma unroll
;     for (int ks = 0; ks < 4; ++ks) qf[ks] = *(const bf16x8*)(QKV + (size_t)tq * QKVW + COL_AQ + head * 128 + ks * 32 + slab * 8);
;     f32x4 sacc[10];
; #pragma unroll
;     for (int jt = 0; jt < 9; ++jt) { int m = mbase + i0 + 16 * jt + n16; m = max(m, 0);
;         const bf16_t* kp = QKV + (size_t)((m << rsh) + p) * QKVW + COL_AK + head * 128 + slab * 8;
;         f32x4 acc = {0.f, 0.f, 0.f, 0.f};
; #pragma unroll
;         for (int ks = 0; ks < 4; ++ks) acc = __builtin_amdgcn_mfma_f32_16x16x32_bf16(*(const bf16x8*)(kp + ks * 32), qf[ks], acc, 0, 0, 0);
;         sacc[jt] = acc; }
	ds_write_b128 v65, v[94:97]
	ds_write_b128 v66, v[98:101]
	ds_write_b128 v67, v[102:105]
	ds_write_b128 v68, v[106:109]
	ds_write_b128 v69, v[110:113]
	ds_write_b128 v70, v[114:117]
	ds_write_b128 v71, v[118:121]
	ds_write_b128 v72, v[122:125]
	v_add_u32_e32 v188, 69632, v65
	v_add_u32_e32 v189, 69632, v66
	v_add_u32_e32 v190, 69632, v67
	v_add_u32_e32 v191, 69632, v68
	v_add_u32_e32 v192, 69632, v69
	v_add_u32_e32 v193, 69632, v70
	v_add_u32_e32 v194, 69632, v71
	ds_write_b128 v188, v[130:133]
	ds_write_b128 v189, v[134:137]
	ds_write_b128 v190, v[138:141]
	ds_write_b128 v191, v[142:145]
	ds_write_b128 v192, v[146:149]
	ds_write_b128 v193, v[150:153]
	ds_write_b128 v194, v[196:199]
	ds_write_b128 v126, v[184:187]
	v_or_b32_e32 v0, s16, v154
	v_lshlrev_b32_e32 v0, s13, v0
	v_add_u32_e32 v52, s19, v0
	v_mov_b64_e32 v[54:55], s[20:21]
	s_movk_i32 s28, 0x3c00
	v_mad_i64_i32 v[0:1], s[16:17], v52, s28, v[54:55]
	s_lshl_b64 s[10:11], s[10:11], 1
	v_lshl_add_u64 v[0:1], v[0:1], 0, s[10:11]
	v_lshl_add_u64 v[0:1], v[0:1], 0, v[160:161]
	s_waitcnt lgkmcnt(0)
	s_barrier
	global_load_dwordx4 v[20:23], v[0:1], off
	global_load_dwordx4 v[16:19], v[0:1], off offset:64
	global_load_dwordx4 v[12:15], v[0:1], off offset:128
	global_load_dwordx4 v[4:7], v[0:1], off offset:192
	v_or_b32_e32 v0, s23, v154
	v_add_u32_e32 v53, s1, v0
	v_max_i32_e32 v0, 0, v53
	v_lshlrev_b32_e32 v0, s13, v0
	v_add_u32_e32 v0, s19, v0
	v_mad_i64_i32 v[0:1], s[16:17], v0, s28, v[54:55]
	v_lshl_add_u64 v[0:1], v[0:1], 0, s[10:11]
	v_lshl_add_u64 v[24:25], v[0:1], 0, v[160:161]
	s_cmp_lg_u32 s5, 0
	v_max_i32_e32 v8, -16, v53
	v_add_lshl_u32 v8, v8, 16, s13
	v_add_u32_e32 v8, s19, v8
	v_mad_i64_i32 v[8:9], s[16:17], v8, s28, v[54:55]
	v_lshl_add_u64 v[8:9], v[8:9], 0, s[10:11]
	v_lshl_add_u64 v[28:29], v[8:9], 0, v[160:161]
	v_max_i32_e32 v24, 0xffffffe0, v53
	v_add_lshl_u32 v24, v24, 32, s13
	v_add_u32_e32 v24, s19, v24
	v_mad_i64_i32 v[24:25], s[16:17], v24, s28, v[54:55]
	v_lshl_add_u64 v[24:25], v[24:25], 0, s[10:11]
	v_lshl_add_u64 v[32:33], v[24:25], 0, v[160:161]
	v_max_i32_e32 v28, 0xffffffd0, v53
	v_add_lshl_u32 v28, v28, 48, s13
	v_add_u32_e32 v28, s19, v28
	v_mad_i64_i32 v[28:29], s[16:17], v28, s28, v[54:55]
	v_lshl_add_u64 v[28:29], v[28:29], 0, s[10:11]
	v_lshl_add_u64 v[36:37], v[28:29], 0, v[160:161]
	v_max_i32_e32 v32, 0xffffffc0, v53
	v_add_lshl_u32 v32, v32, 64, s13
	v_add_u32_e32 v32, s19, v32
	v_mad_i64_i32 v[32:33], s[16:17], v32, s28, v[54:55]
	v_lshl_add_u64 v[32:33], v[32:33], 0, s[10:11]
	v_lshl_add_u64 v[40:41], v[32:33], 0, v[160:161]
	v_max_i32_e32 v36, 0xffffffb0, v53
	v_add_u32_e32 v36, 0x50, v36
	v_lshlrev_b32_e32 v36, s13, v36
	v_add_u32_e32 v36, s19, v36
	v_mad_i64_i32 v[36:37], s[16:17], v36, s28, v[54:55]
	v_lshl_add_u64 v[36:37], v[36:37], 0, s[10:11]
	v_lshl_add_u64 v[44:45], v[36:37], 0, v[160:161]
	v_max_i32_e32 v40, 0xffffffa0, v53
	v_add_u32_e32 v40, 0x60, v40
	v_lshlrev_b32_e32 v40, s13, v40
	v_add_u32_e32 v40, s19, v40
	v_mad_i64_i32 v[40:41], s[16:17], v40, s28, v[54:55]
	v_lshl_add_u64 v[40:41], v[40:41], 0, s[10:11]
	v_lshl_add_u64 v[74:75], v[40:41], 0, v[160:161]
	v_max_i32_e32 v44, 0xffffff90, v53
	v_add_u32_e32 v44, 0x70, v44
	v_lshlrev_b32_e32 v44, s13, v44
	v_add_u32_e32 v44, s19, v44
	v_mad_i64_i32 v[44:45], s[16:17], v44, s28, v[54:55]
	v_lshl_add_u64 v[44:45], v[44:45], 0, s[10:11]
	v_lshl_add_u64 v[78:79], v[44:45], 0, v[160:161]
	v_max_i32_e32 v53, 0xffffff80, v53
	v_add_u32_e32 v53, 0x80, v53
	v_lshlrev_b32_e32 v53, s13, v53
	v_add_u32_e32 v53, s19, v53
	v_mad_i64_i32 v[54:55], s[16:17], v53, s28, v[54:55]
	v_lshl_add_u64 v[54:55], v[54:55], 0, s[10:11]
	v_lshl_add_u64 v[54:55], v[54:55], 0, v[160:161]
	s_cselect_b64 s[10:11], -1, 0
	v_add_u32_e32 v126, s1, v154
	v_mul_u32_u24_e32 v127, 0x110, v126
	v_add_u32_e32 v127, v127, v160
	v_add_u32_e32 v127, 69632, v127
	v_add_u32_e32 v128, 112, v126
	v_cmp_gt_u32_e32 vcc, 225, v128
	v_mov_b32_e32 v128, 31216
	v_mov_b32_e32 v129, 30464
	s_nop 0
	v_cndmask_b32_e32 v128, v128, v129, vcc
	v_add_u32_e32 v128, v128, v127
	v_add_u32_e32 v129, 128, v126
	v_cmp_gt_u32_e32 vcc, 225, v129
	v_mov_b32_e32 v129, 35568
	v_mov_b32_e32 v125, 34816
	s_nop 0
	v_cndmask_b32_e32 v129, v129, v125, vcc
	v_add_u32_e32 v129, v129, v127
	s_waitcnt vmcnt(0)
	ds_read_b128 v[0:3], v127 offset:0
	ds_read_b128 v[98:101], v127 offset:64
	ds_read_b128 v[102:105], v127 offset:128
	ds_read_b128 v[106:109], v127 offset:192
	ds_read_b128 v[8:11], v127 offset:4352
	ds_read_b128 v[114:117], v127 offset:4416
	ds_read_b128 v[130:133], v127 offset:4480
	ds_read_b128 v[134:137], v127 offset:4544
	s_waitcnt lgkmcnt(4)
	v_mfma_f32_16x16x32_bf16 v[0:3], v[0:3], v[20:23], 0
	v_mfma_f32_16x16x32_bf16 v[0:3], v[98:101], v[16:19], v[0:3]
	v_mfma_f32_16x16x32_bf16 v[0:3], v[102:105], v[12:15], v[0:3]
	v_mfma_f32_16x16x32_bf16 v[0:3], v[106:109], v[4:7], v[0:3]
	ds_read_b128 v[24:27], v127 offset:8704
	ds_read_b128 v[98:101], v127 offset:8768
	ds_read_b128 v[102:105], v127 offset:8832
	ds_read_b128 v[106:109], v127 offset:8896
	s_waitcnt lgkmcnt(4)
	v_mfma_f32_16x16x32_bf16 v[8:11], v[8:11], v[20:23], 0
	v_mfma_f32_16x16x32_bf16 v[8:11], v[114:117], v[16:19], v[8:11]
	v_mfma_f32_16x16x32_bf16 v[8:11], v[130:133], v[12:15], v[8:11]
	v_mfma_f32_16x16x32_bf16 v[8:11], v[134:137], v[4:7], v[8:11]
	ds_read_b128 v[28:31], v127 offset:13056
	ds_read_b128 v[114:117], v127 offset:13120
	ds_read_b128 v[130:133], v127 offset:13184
	ds_read_b128 v[134:137], v127 offset:13248
	s_waitcnt lgkmcnt(4)
; __device__ __forceinline__ void dilated_block(const bf16_t* QKV, bf16_t* OG, float* LSE, LAS unsigned char* lds, int u, int tid) {
;     ...
; #pragma unroll
;     for (int jt = 0; jt < 9; ++jt) { int m = mbase + i0 + 16 * jt + n16; m = max(m, 0);
;         const bf16_t* kp = QKV + (size_t)((m << rsh) + p) * QKVW + COL_AK + head * 128 + slab * 8;
;         f32x4 acc = {0.f, 0.f, 0.f, 0.f};
; #pragma unroll
;         for (int ks = 0; ks < 4; ++ks) acc = __builtin_amdgcn_mfma_f32_16x16x32_bf16(*(const bf16x8*)(kp + ks * 32), qf[ks], acc, 0, 0, 0);
;         sacc[jt] = acc; }
;     float mx = -INFINITY;
; #pragma unroll
;     for (int jt = 0; jt < 9; ++jt)
; #pragma unroll
;         for (int i = 0; i < 4; ++i) { const int d = 128 + n16 - 16 * jt - 4 * slab - i, kk = i0 + 16 * jt + 4 * slab + i;
;             const bool ok = (d >= 0) && (d <= 128) && (nb > 0 || kk >= 128);
;             const float s = ok ? sacc[jt][i] * 0.08838834764831845f : -INFINITY; sacc[jt][i] = s; mx = fmaxf(mx, s); }
	v_mfma_f32_16x16x32_bf16 v[24:27], v[24:27], v[20:23], 0
	v_mfma_f32_16x16x32_bf16 v[24:27], v[98:101], v[16:19], v[24:27]
	v_mfma_f32_16x16x32_bf16 v[24:27], v[102:105], v[12:15], v[24:27]
	v_mfma_f32_16x16x32_bf16 v[24:27], v[106:109], v[4:7], v[24:27]
	ds_read_b128 v[32:35], v127 offset:17408
	ds_read_b128 v[98:101], v127 offset:17472
	ds_read_b128 v[102:105], v127 offset:17536
	ds_read_b128 v[106:109], v127 offset:17600
	s_waitcnt lgkmcnt(4)
	v_mfma_f32_16x16x32_bf16 v[28:31], v[28:31], v[20:23], 0
	v_mfma_f32_16x16x32_bf16 v[28:31], v[114:117], v[16:19], v[28:31]
	v_mfma_f32_16x16x32_bf16 v[28:31], v[130:133], v[12:15], v[28:31]
	v_mfma_f32_16x16x32_bf16 v[28:31], v[134:137], v[4:7], v[28:31]
	ds_read_b128 v[36:39], v127 offset:21760
	ds_read_b128 v[114:117], v127 offset:21824
	ds_read_b128 v[130:133], v127 offset:21888
	ds_read_b128 v[134:137], v127 offset:21952
	s_waitcnt lgkmcnt(4)
	v_mfma_f32_16x16x32_bf16 v[32:35], v[32:35], v[20:23], 0
	v_mfma_f32_16x16x32_bf16 v[32:35], v[98:101], v[16:19], v[32:35]
	v_mfma_f32_16x16x32_bf16 v[32:35], v[102:105], v[12:15], v[32:35]
	v_mfma_f32_16x16x32_bf16 v[32:35], v[106:109], v[4:7], v[32:35]
	ds_read_b128 v[40:43], v127 offset:26112
	ds_read_b128 v[98:101], v127 offset:26176
	ds_read_b128 v[102:105], v127 offset:26240
	ds_read_b128 v[106:109], v127 offset:26304
	s_waitcnt lgkmcnt(4)
	v_mfma_f32_16x16x32_bf16 v[36:39], v[36:39], v[20:23], 0
	v_mfma_f32_16x16x32_bf16 v[36:39], v[114:117], v[16:19], v[36:39]
	v_mfma_f32_16x16x32_bf16 v[36:39], v[130:133], v[12:15], v[36:39]
	v_mfma_f32_16x16x32_bf16 v[36:39], v[134:137], v[4:7], v[36:39]
	ds_read_b128 v[44:47], v128 offset:0
	ds_read_b128 v[114:117], v128 offset:64
	ds_read_b128 v[130:133], v128 offset:128
	ds_read_b128 v[134:137], v128 offset:192
	s_waitcnt lgkmcnt(4)
	v_mfma_f32_16x16x32_bf16 v[40:43], v[40:43], v[20:23], 0
	v_mfma_f32_16x16x32_bf16 v[40:43], v[98:101], v[16:19], v[40:43]
	v_mfma_f32_16x16x32_bf16 v[40:43], v[102:105], v[12:15], v[40:43]
	v_mfma_f32_16x16x32_bf16 v[40:43], v[106:109], v[4:7], v[40:43]
	ds_read_b128 v[94:97], v129 offset:0
	ds_read_b128 v[98:101], v129 offset:64
	ds_read_b128 v[102:105], v129 offset:128
	ds_read_b128 v[106:109], v129 offset:192
	s_waitcnt lgkmcnt(4)
	v_mfma_f32_16x16x32_bf16 v[44:47], v[44:47], v[20:23], 0
	v_mfma_f32_16x16x32_bf16 v[44:47], v[114:117], v[16:19], v[44:47]
	v_mfma_f32_16x16x32_bf16 v[44:47], v[130:133], v[12:15], v[44:47]
	v_mfma_f32_16x16x32_bf16 v[44:47], v[134:137], v[4:7], v[44:47]
	s_waitcnt lgkmcnt(0)
	v_mfma_f32_16x16x32_bf16 v[20:23], v[94:97], v[20:23], 0
	v_mfma_f32_16x16x32_bf16 v[16:19], v[98:101], v[16:19], v[20:23]
	v_mfma_f32_16x16x32_bf16 v[12:15], v[102:105], v[12:15], v[16:19]
	v_mfma_f32_16x16x32_bf16 v[4:7], v[106:109], v[4:7], v[12:15]
	s_nop 7
	s_nop 2
	v_or_b32_e32 v14, s1, v49
	v_mov_b32_e32 v12, 0xff800000
	v_mov_b32_e32 v13, 0xff800000
	s_and_saveexec_b64 s[16:17], s[42:43]
	v_or_b32_e32 v13, 2, v14
	s_movk_i32 s5, 0x7f
	v_cmp_lt_i32_e32 vcc, s5, v13
	v_mul_f32_e32 v2, 0x3db504f3, v2
	s_or_b64 vcc, s[10:11], vcc
	v_cndmask_b32_e32 v13, v208, v2, vcc
	s_or_b64 exec, exec, s[16:17]
	s_and_saveexec_b64 s[16:17], s[44:45]
	v_or_b32_e32 v2, 3, v14
	s_movk_i32 s5, 0x7f
	v_cmp_lt_i32_e32 vcc, s5, v2
	v_mul_f32_e32 v2, 0x3db504f3, v3
	s_or_b64 vcc, s[10:11], vcc
	v_cndmask_b32_e32 v12, v208, v2, vcc
	s_or_b64 exec, exec, s[16:17]
	s_movk_i32 s5, 0x7f
	v_cmp_lt_i32_e32 vcc, s5, v14
	s_or_b64 s[16:17], s[10:11], vcc
	v_mul_f32_e32 v0, 0x3db504f3, v0
	s_and_b64 vcc, s[38:39], s[16:17]
	s_movk_i32 s5, 0x7e
	v_cndmask_b32_e32 v0, v208, v0, vcc
	v_cmp_lt_i32_e32 vcc, s5, v14
	s_or_b64 s[16:17], s[10:11], vcc
	v_mul_f32_e32 v1, 0x3db504f3, v1
	s_and_b64 vcc, s[40:41], s[16:17]
	v_cndmask_b32_e32 v1, v208, v1, vcc
	s_mov_b32 s5, 0xff800000
	v_max3_f32 v2, v0, s5, v1
	s_movk_i32 s5, 0x6f
	v_cmp_lt_i32_e32 vcc, s5, v14
	v_mul_f32_e32 v3, 0x3db504f3, v8
	s_or_b64 vcc, s[10:11], vcc
	s_movk_i32 s5, 0x6e
	v_cndmask_b32_e32 v3, v208, v3, vcc
	v_cmp_lt_i32_e32 vcc, s5, v14
	v_mul_f32_e32 v8, 0x3db504f3, v9
	s_or_b64 vcc, s[10:11], vcc
	s_movk_i32 s5, 0x6d
	v_cndmask_b32_e32 v8, v208, v8, vcc
	v_cmp_lt_i32_e32 vcc, s5, v14
	v_mul_f32_e32 v9, 0x3db504f3, v10
	s_or_b64 vcc, s[10:11], vcc
	s_movk_i32 s5, 0x6c
	v_cndmask_b32_e32 v9, v208, v9, vcc
	v_cmp_lt_i32_e32 vcc, s5, v14
	v_mul_f32_e32 v10, 0x3db504f3, v11
	s_or_b64 vcc, s[10:11], vcc
	s_movk_i32 s5, 0x5f
	v_cndmask_b32_e32 v10, v208, v10, vcc
	v_cmp_lt_i32_e32 vcc, s5, v14
	v_mul_f32_e32 v11, 0x3db504f3, v24
	s_or_b64 vcc, s[10:11], vcc
	s_movk_i32 s5, 0x5e
	v_cndmask_b32_e32 v11, v208, v11, vcc
	v_cmp_lt_i32_e32 vcc, s5, v14
	v_mul_f32_e32 v15, 0x3db504f3, v25
	s_or_b64 vcc, s[10:11], vcc
	s_movk_i32 s5, 0x5d
	v_cndmask_b32_e32 v15, v208, v15, vcc
	v_cmp_lt_i32_e32 vcc, s5, v14
	v_mul_f32_e32 v16, 0x3db504f3, v26
	s_or_b64 vcc, s[10:11], vcc
	s_movk_i32 s5, 0x5c
	v_cndmask_b32_e32 v16, v208, v16, vcc
	v_cmp_lt_i32_e32 vcc, s5, v14
	v_mul_f32_e32 v17, 0x3db504f3, v27
	s_or_b64 vcc, s[10:11], vcc
	s_movk_i32 s5, 0x4f
	v_cndmask_b32_e32 v17, v208, v17, vcc
	v_cmp_lt_i32_e32 vcc, s5, v14
	v_mul_f32_e32 v18, 0x3db504f3, v28
	s_or_b64 vcc, s[10:11], vcc
	s_movk_i32 s5, 0x4e
	v_cndmask_b32_e32 v18, v208, v18, vcc
	v_cmp_lt_i32_e32 vcc, s5, v14
	v_mul_f32_e32 v19, 0x3db504f3, v29
	s_or_b64 vcc, s[10:11], vcc
	s_movk_i32 s5, 0x4d
	v_cndmask_b32_e32 v19, v208, v19, vcc
	v_cmp_lt_i32_e32 vcc, s5, v14
	v_mul_f32_e32 v20, 0x3db504f3, v30
	s_or_b64 vcc, s[10:11], vcc
	s_movk_i32 s5, 0x4c
	v_cndmask_b32_e32 v20, v208, v20, vcc
	v_cmp_lt_i32_e32 vcc, s5, v14
	v_mul_f32_e32 v21, 0x3db504f3, v31
	s_or_b64 vcc, s[10:11], vcc
; __device__ __forceinline__ void pl32(unsigned a, unsigned b, unsigned& ra, unsigned& rb) { asm volatile("" : "+v"(b)); auto r = __builtin_amdgcn_permlane32_swap(a, b, false, false); ra = r[0]; rb = r[1]; asm volatile("" : "+v"(ra), "+v"(rb)); }
; __device__ __forceinline__ void pl16(unsigned a, unsigned b, unsigned& ra, unsigned& rb) { asm volatile("" : "+v"(b)); auto r = __builtin_amdgcn_permlane16_swap(a, b, false, false); ra = r[0]; rb = r[1]; asm volatile("" : "+v"(ra), "+v"(rb)); }
; __device__ __forceinline__ void dilated_block(const bf16_t* QKV, bf16_t* OG, float* LSE, LAS unsigned char* lds, int u, int tid) {
;     ...
;     float mx = -INFINITY;
; #pragma unroll
;     for (int jt = 0; jt < 9; ++jt)
; #pragma unroll
;         for (int i = 0; i < 4; ++i) { const int d = 128 + n16 - 16 * jt - 4 * slab - i, kk = i0 + 16 * jt + 4 * slab + i;
;             const bool ok = (d >= 0) && (d <= 128) && (nb > 0 || kk >= 128);
;             const float s = ok ? sacc[jt][i] * 0.08838834764831845f : -INFINITY; sacc[jt][i] = s; mx = fmaxf(mx, s); }
;     { unsigned x, y; pl16(__builtin_bit_cast(unsigned, mx), __builtin_bit_cast(unsigned, mx), x, y); mx = fmaxf(__builtin_bit_cast(float, x), __builtin_bit_cast(float, y));
;       pl32(__builtin_bit_cast(unsigned, mx), __builtin_bit_cast(unsigned, mx), x, y); mx = fmaxf(__builtin_bit_cast(float, x), __builtin_bit_cast(float, y)); }
;     float lsum = 0.f;
; #pragma unroll
;     for (int jt = 0; jt < 9; ++jt)
; #pragma unroll
;         for (int i = 0; i < 4; ++i) { const float pe = __expf(sacc[jt][i] - mx); sacc[jt][i] = pe; lsum += pe; }
	v_cndmask_b32_e32 v28, v208, v21, vcc
	v_cmp_lt_i32_e32 vcc, 63, v14
	v_mul_f32_e32 v21, 0x3db504f3, v32
	s_or_b64 vcc, s[10:11], vcc
	v_cndmask_b32_e32 v54, v208, v21, vcc
	v_cmp_lt_i32_e32 vcc, 62, v14
	v_mul_f32_e32 v21, 0x3db504f3, v33
	s_or_b64 vcc, s[10:11], vcc
	v_cndmask_b32_e32 v55, v208, v21, vcc
	v_cmp_lt_i32_e32 vcc, 61, v14
	v_mul_f32_e32 v21, 0x3db504f3, v34
	s_or_b64 vcc, s[10:11], vcc
	v_cndmask_b32_e32 v73, v208, v21, vcc
	v_cmp_lt_i32_e32 vcc, 60, v14
	v_mul_f32_e32 v21, 0x3db504f3, v35
	s_or_b64 vcc, s[10:11], vcc
	v_cndmask_b32_e32 v74, v208, v21, vcc
	v_cmp_lt_i32_e32 vcc, 47, v14
	v_mul_f32_e32 v21, 0x3db504f3, v36
	s_or_b64 vcc, s[10:11], vcc
	v_cndmask_b32_e32 v75, v208, v21, vcc
	v_cmp_lt_i32_e32 vcc, 46, v14
	v_mul_f32_e32 v21, 0x3db504f3, v37
	s_or_b64 vcc, s[10:11], vcc
	v_cndmask_b32_e32 v76, v208, v21, vcc
	v_cmp_lt_i32_e32 vcc, 45, v14
	v_mul_f32_e32 v21, 0x3db504f3, v38
	s_or_b64 vcc, s[10:11], vcc
	v_cndmask_b32_e32 v38, v208, v21, vcc
	v_cmp_lt_i32_e32 vcc, 44, v14
	v_mul_f32_e32 v21, 0x3db504f3, v39
	s_or_b64 vcc, s[10:11], vcc
	v_cndmask_b32_e32 v39, v208, v21, vcc
	v_cmp_lt_i32_e32 vcc, 31, v14
	v_mul_f32_e32 v21, 0x3db504f3, v40
	s_or_b64 vcc, s[10:11], vcc
	v_cndmask_b32_e32 v40, v208, v21, vcc
	v_cmp_lt_i32_e32 vcc, 30, v14
	v_mul_f32_e32 v21, 0x3db504f3, v41
	s_or_b64 vcc, s[10:11], vcc
	v_cndmask_b32_e32 v41, v208, v21, vcc
	v_cmp_lt_i32_e32 vcc, 29, v14
	v_mul_f32_e32 v21, 0x3db504f3, v42
	s_or_b64 vcc, s[10:11], vcc
	v_cndmask_b32_e32 v42, v208, v21, vcc
	v_cmp_lt_i32_e32 vcc, 28, v14
	v_mul_f32_e32 v21, 0x3db504f3, v43
	s_or_b64 vcc, s[10:11], vcc
	v_cndmask_b32_e32 v43, v208, v21, vcc
	v_cmp_lt_i32_e32 vcc, 15, v14
	v_mul_f32_e32 v21, 0x3db504f3, v44
	s_or_b64 vcc, s[10:11], vcc
	v_cndmask_b32_e32 v44, v208, v21, vcc
	v_cmp_lt_i32_e32 vcc, 14, v14
	v_mul_f32_e32 v21, 0x3db504f3, v45
	s_or_b64 vcc, s[10:11], vcc
	v_cndmask_b32_e32 v45, v208, v21, vcc
	v_cmp_lt_i32_e32 vcc, 13, v14
	v_mul_f32_e32 v21, 0x3db504f3, v46
	s_or_b64 vcc, s[10:11], vcc
	v_max3_f32 v2, v2, v13, v12
	v_cndmask_b32_e32 v46, v208, v21, vcc
	v_cmp_lt_i32_e32 vcc, 12, v14
	v_max3_f32 v2, v2, v3, v8
	s_or_b64 vcc, s[10:11], vcc
	v_max3_f32 v2, v2, v9, v10
	s_cmp_gt_i32 s22, -1
	v_max3_f32 v2, v2, v11, v15
	s_cselect_b64 s[16:17], -1, 0
	v_max3_f32 v2, v2, v16, v17
	v_mul_f32_e32 v21, 0x3db504f3, v47
	s_or_b64 s[16:17], s[10:11], s[16:17]
	v_max3_f32 v2, v2, v18, v19
	v_cndmask_b32_e32 v47, v208, v21, vcc
	v_mul_f32_e32 v4, 0x3db504f3, v4
	s_and_b64 vcc, s[46:47], s[16:17]
	v_max3_f32 v2, v2, v20, v28
	v_cndmask_b32_e32 v4, v208, v4, vcc
	v_cmp_lt_i32_e32 vcc, -2, v14
	v_max3_f32 v2, v2, v54, v55
	s_or_b64 s[16:17], s[10:11], vcc
	v_max3_f32 v2, v2, v73, v74
	v_mul_f32_e32 v5, 0x3db504f3, v5
	s_and_b64 vcc, s[48:49], s[16:17]
	v_max3_f32 v2, v2, v75, v76
	v_cndmask_b32_e32 v77, v208, v5, vcc
	v_cmp_lt_i32_e32 vcc, -3, v14
	v_max3_f32 v2, v2, v38, v39
	s_or_b64 s[16:17], s[10:11], vcc
	v_max3_f32 v2, v2, v40, v41
	v_mul_f32_e32 v5, 0x3db504f3, v6
	s_and_b64 vcc, s[50:51], s[16:17]
	v_max3_f32 v2, v2, v42, v43
	v_cndmask_b32_e32 v78, v208, v5, vcc
	v_cmp_lt_i32_e32 vcc, -4, v14
	v_max3_f32 v2, v2, v44, v45
	s_or_b64 s[10:11], s[10:11], vcc
	v_max3_f32 v2, v2, v46, v47
	v_mul_f32_e32 v5, 0x3db504f3, v7
	s_and_b64 vcc, s[52:53], s[10:11]
	v_max3_f32 v2, v2, v4, v77
	v_cndmask_b32_e32 v79, v208, v5, vcc
	v_max3_f32 v2, v2, v78, v79
	v_mov_b32_e32 v5, v2
	v_ashrrev_i32_e32 v53, 31, v52
	s_nop 0
	v_permlane16_swap_b32_e32 v2, v5
	s_nop 0
	v_max_f32_e32 v5, v5, v5
	v_max_f32_e32 v2, v2, v2
	v_max_f32_e32 v2, v2, v5
	v_mov_b32_e32 v5, v2
	s_nop 1
	v_permlane32_swap_b32_e32 v2, v5
	s_nop 0
	v_max_f32_e32 v5, v5, v5
	v_max_f32_e32 v2, v2, v2
	v_max_f32_e32 v37, v2, v5
	v_sub_f32_e32 v0, v0, v37
	v_mul_f32_e32 v0, 0x3fb8aa3b, v0
	v_exp_f32_e32 v29, v0
	v_sub_f32_e32 v0, v1, v37
	v_sub_f32_e32 v1, v3, v37
	v_mul_f32_e32 v1, 0x3fb8aa3b, v1
	v_exp_f32_e32 v32, v1
	v_sub_f32_e32 v1, v8, v37
	v_mul_f32_e32 v1, 0x3fb8aa3b, v1
	v_exp_f32_e32 v35, v1
	v_sub_f32_e32 v1, v9, v37
	v_mul_f32_e32 v1, 0x3fb8aa3b, v1
	v_exp_f32_e32 v34, v1
	v_sub_f32_e32 v1, v10, v37
	v_mul_f32_e32 v1, 0x3fb8aa3b, v1
	v_exp_f32_e32 v36, v1
	v_sub_f32_e32 v1, v11, v37
	v_mul_f32_e32 v1, 0x3fb8aa3b, v1
	v_exp_f32_e32 v21, v1
	v_sub_f32_e32 v1, v15, v37
	v_mul_f32_e32 v1, 0x3fb8aa3b, v1
	v_exp_f32_e32 v23, v1
	v_sub_f32_e32 v1, v16, v37
; __device__ __forceinline__ float swap32_sum(float a, float b) { unsigned x, y; pl32(__builtin_bit_cast(unsigned, a), __builtin_bit_cast(unsigned, b), x, y); return __builtin_bit_cast(float, x) + __builtin_bit_cast(float, y); }
; __device__ __forceinline__ float swap16_sum(float a, float b) { unsigned x, y; pl16(__builtin_bit_cast(unsigned, a), __builtin_bit_cast(unsigned, b), x, y); return __builtin_bit_cast(float, x) + __builtin_bit_cast(float, y); }
; __device__ __forceinline__ void dilated_block(const bf16_t* QKV, bf16_t* OG, float* LSE, LAS unsigned char* lds, int u, int tid) {
;     ...
;     float lsum = 0.f;
; #pragma unroll
;     for (int jt = 0; jt < 9; ++jt)
; #pragma unroll
;         for (int i = 0; i < 4; ++i) { const float pe = __expf(sacc[jt][i] - mx); sacc[jt][i] = pe; lsum += pe; }
;     sacc[9] = (f32x4){0.f, 0.f, 0.f, 0.f};
;     lsum = swap16_sum(lsum, lsum); lsum = swap32_sum(lsum, lsum);
;     if (slab == 0) LSE[(size_t)tq * 12 + head] = mx + __logf(lsum);
	v_mul_f32_e32 v1, 0x3fb8aa3b, v1
	v_exp_f32_e32 v22, v1
	v_sub_f32_e32 v1, v17, v37
	v_mul_f32_e32 v1, 0x3fb8aa3b, v1
	v_exp_f32_e32 v25, v1
	v_sub_f32_e32 v1, v18, v37
	v_mul_f32_e32 v1, 0x3fb8aa3b, v1
	v_exp_f32_e32 v24, v1
	v_sub_f32_e32 v1, v19, v37
	v_mul_f32_e32 v1, 0x3fb8aa3b, v1
	v_exp_f32_e32 v27, v1
	v_sub_f32_e32 v1, v20, v37
	v_mul_f32_e32 v1, 0x3fb8aa3b, v1
	v_exp_f32_e32 v26, v1
	v_sub_f32_e32 v1, v28, v37
	v_mul_f32_e32 v1, 0x3fb8aa3b, v1
	v_exp_f32_e32 v28, v1
	v_sub_f32_e32 v1, v54, v37
	v_mul_f32_e32 v0, 0x3fb8aa3b, v0
	v_mul_f32_e32 v1, 0x3fb8aa3b, v1
	v_exp_f32_e32 v31, v0
	v_sub_f32_e32 v0, v13, v37
	v_exp_f32_e32 v13, v1
	v_sub_f32_e32 v1, v55, v37
	v_mul_f32_e32 v0, 0x3fb8aa3b, v0
	v_mul_f32_e32 v1, 0x3fb8aa3b, v1
	v_exp_f32_e32 v30, v0
	v_sub_f32_e32 v0, v12, v37
	v_exp_f32_e32 v15, v1
	v_sub_f32_e32 v1, v73, v37
	v_mul_f32_e32 v0, 0x3fb8aa3b, v0
	v_mul_f32_e32 v1, 0x3fb8aa3b, v1
	v_exp_f32_e32 v33, v0
	v_exp_f32_e32 v14, v1
	v_sub_f32_e32 v1, v74, v37
	v_add_f32_e32 v0, 0, v29
	v_mul_f32_e32 v1, 0x3fb8aa3b, v1
	v_add_f32_e32 v0, v31, v0
	v_exp_f32_e32 v17, v1
	v_sub_f32_e32 v1, v75, v37
	v_add_f32_e32 v0, v30, v0
	v_mul_f32_e32 v1, 0x3fb8aa3b, v1
	v_add_f32_e32 v0, v33, v0
	v_exp_f32_e32 v16, v1
	v_sub_f32_e32 v1, v76, v37
	v_add_f32_e32 v0, v32, v0
	v_mul_f32_e32 v1, 0x3fb8aa3b, v1
	v_add_f32_e32 v0, v35, v0
	v_exp_f32_e32 v19, v1
	v_sub_f32_e32 v1, v38, v37
	v_add_f32_e32 v0, v34, v0
	v_mul_f32_e32 v1, 0x3fb8aa3b, v1
	v_add_f32_e32 v0, v36, v0
	v_exp_f32_e32 v18, v1
	v_sub_f32_e32 v1, v39, v37
	v_add_f32_e32 v0, v21, v0
	v_mul_f32_e32 v1, 0x3fb8aa3b, v1
	v_add_f32_e32 v0, v23, v0
	v_exp_f32_e32 v20, v1
	v_sub_f32_e32 v1, v40, v37
	v_add_f32_e32 v0, v22, v0
	v_mul_f32_e32 v1, 0x3fb8aa3b, v1
	v_add_f32_e32 v0, v25, v0
	v_exp_f32_e32 v5, v1
	v_sub_f32_e32 v1, v41, v37
	v_add_f32_e32 v0, v24, v0
	v_mul_f32_e32 v1, 0x3fb8aa3b, v1
	v_add_f32_e32 v0, v27, v0
	v_exp_f32_e32 v7, v1
	v_sub_f32_e32 v1, v42, v37
	v_add_f32_e32 v0, v26, v0
	v_mul_f32_e32 v1, 0x3fb8aa3b, v1
	v_add_f32_e32 v0, v28, v0
	v_exp_f32_e32 v6, v1
	v_sub_f32_e32 v1, v43, v37
	v_add_f32_e32 v0, v13, v0
	v_mul_f32_e32 v1, 0x3fb8aa3b, v1
	v_add_f32_e32 v0, v15, v0
	v_exp_f32_e32 v9, v1
	v_sub_f32_e32 v1, v44, v37
	v_add_f32_e32 v0, v14, v0
	v_mul_f32_e32 v1, 0x3fb8aa3b, v1
	v_add_f32_e32 v0, v17, v0
	v_exp_f32_e32 v8, v1
	v_sub_f32_e32 v1, v45, v37
	v_add_f32_e32 v0, v16, v0
	v_mul_f32_e32 v1, 0x3fb8aa3b, v1
	v_add_f32_e32 v0, v19, v0
	v_exp_f32_e32 v11, v1
	v_sub_f32_e32 v1, v46, v37
	v_add_f32_e32 v0, v18, v0
	v_mul_f32_e32 v1, 0x3fb8aa3b, v1
	v_add_f32_e32 v0, v20, v0
	v_exp_f32_e32 v10, v1
	v_sub_f32_e32 v1, v47, v37
	v_add_f32_e32 v0, v5, v0
	v_mul_f32_e32 v1, 0x3fb8aa3b, v1
	v_add_f32_e32 v0, v7, v0
	v_exp_f32_e32 v12, v1
	v_sub_f32_e32 v1, v4, v37
	v_add_f32_e32 v0, v6, v0
	v_mul_f32_e32 v1, 0x3fb8aa3b, v1
	v_add_f32_e32 v0, v9, v0
	v_exp_f32_e32 v2, v1
	v_sub_f32_e32 v1, v77, v37
	v_add_f32_e32 v0, v8, v0
	v_mul_f32_e32 v1, 0x3fb8aa3b, v1
	v_sub_f32_e32 v3, v78, v37
	v_add_f32_e32 v0, v11, v0
	v_exp_f32_e32 v1, v1
	v_mul_f32_e32 v3, 0x3fb8aa3b, v3
	v_sub_f32_e32 v4, v79, v37
	v_add_f32_e32 v0, v10, v0
	v_exp_f32_e32 v3, v3
	v_mul_f32_e32 v4, 0x3fb8aa3b, v4
	v_add_f32_e32 v0, v12, v0
	v_exp_f32_e32 v4, v4
	v_add_f32_e32 v0, v2, v0
	v_add_f32_e32 v0, v1, v0
	v_add_f32_e32 v0, v3, v0
	v_add_f32_e32 v0, v4, v0
	v_mov_b32_e32 v38, v0
	s_nop 1
	v_permlane16_swap_b32_e32 v0, v38
	s_nop 0
	v_add_f32_e32 v0, v0, v38
	v_mov_b32_e32 v38, v0
	s_nop 1
	v_permlane32_swap_b32_e32 v0, v38
	s_nop 0
	v_add_f32_e32 v0, v0, v38
	s_and_saveexec_b64 s[10:11], s[54:55]
	s_cbranch_execz .LBB0_196
	s_mov_b32 s5, 0x800000
	v_cmp_gt_f32_e32 vcc, s5, v0
	s_mov_b32 s5, 0x3f317217
	v_readlane_b32 s16, v251, 19
	v_cndmask_b32_e64 v38, 0, 32, vcc
	v_ldexp_f32 v38, v0, v38
	v_log_f32_e32 v38, v38
	v_cndmask_b32_e32 v39, 0, v209, vcc
	v_readlane_b32 s17, v251, 20
	v_mul_f32_e32 v40, 0x3f317217, v38
	v_fma_f32 v40, v38, s5, -v40
	v_fmac_f32_e32 v40, 0x3377d1cf, v38
	s_mov_b32 s5, 0x7f800000
	v_fmac_f32_e32 v40, 0x3f317217, v38
	v_cmp_lt_f32_e64 vcc, |v38|, s5
	s_ashr_i32 s5, s4, 31
	s_nop 0
	v_cndmask_b32_e32 v38, v38, v40, vcc
	v_sub_f32_e32 v38, v38, v39
	v_add_f32_e32 v37, v37, v38
	v_mad_i64_i32 v[38:39], s[16:17], v52, 48, s[16:17]
	v_lshl_add_u64 v[38:39], s[4:5], 2, v[38:39]
	global_store_dword v[38:39], v37, off
	s_branch .LBB0_196
